# T10 transpose-read V staging also in the two SWA-latent attention tile bodies
# baseline (speedup 1.0000x reference)
.LBB0_345:
	global_load_dwordx4 v[80:83], v[80:81], off
	s_nop 0
	global_load_dwordx4 v[84:87], v[84:85], off
	s_nop 0
	global_load_dwordx4 v[104:107], v[108:109], off offset:16
	s_nop 0
	global_load_dwordx4 v[108:111], v[108:109], off
	s_barrier
	ds_write_b128 v125, v[32:35]
	ds_write_b128 v126, v[36:39]
	v_and_b32_e32 v223, 0xff, v160
	v_lshrrev_b32_e32 v224, 2, v223
	v_and_b32_e32 v225, 3, v223
	v_lshrrev_b32_e32 v226, 1, v225
	v_bfe_u32 v227, v224, 1, 1
	v_xor_b32_e32 v226, v226, v227
	v_lshlrev_b32_e32 v226, 6, v226
	v_and_b32_e32 v225, 1, v225
	v_lshl_or_b32 v226, v225, 5, v226
	v_lshl_add_u32 v226, v224, 7, v226
	v_add_u32_e32 v223, s78, v226
	v_and_b32_e32 v226, 63, v160
	v_lshrrev_b32_e32 v224, 5, v226
	v_bfe_u32 v227, v226, 2, 2
	v_lshl_add_u32 v224, v224, 2, v227
	v_lshlrev_b32_e32 v224, 7, v224
	v_bfe_u32 v227, v226, 3, 1
	v_lshl_or_b32 v224, v227, 6, v224
	v_bfe_u32 v227, v226, 4, 1
	v_lshl_or_b32 v224, v227, 5, v224
	v_and_b32_e32 v227, 3, v226
	v_lshl_or_b32 v224, v227, 3, v224
	v_add_u32_e32 v224, s78, v224
	v_xor_b32_e32 v225, 64, v224
	ds_write_b128 v223, v[40:43] offset:8192
	ds_write_b128 v223, v[44:47] offset:8208
	s_waitcnt lgkmcnt(0)
	s_barrier
	ds_read_b128 v[32:35], v124
	ds_read_b128 v[48:51], v124 offset:4096
	s_waitcnt lgkmcnt(1)
	v_mfma_f32_32x32x16_bf16 v[32:47], v[32:35], v[76:79], 0
	ds_read_b128 v[144:147], v123
	ds_read_b128 v[148:151], v123 offset:4096
	s_add_i32 s4, s12, s13
	s_addk_i32 s4, 0xff80
	s_cmp_gt_i32 s4, -1
	v_cndmask_b32_e64 v134, 0, 1, s[0:1]
	v_add_u32_e32 v143, s13, v138
	s_cselect_b64 s[8:9], -1, 0
	s_waitcnt lgkmcnt(2)
	v_mfma_f32_32x32x16_bf16 v[48:63], v[48:51], v[76:79], 0
	v_cmp_ne_u32_e64 s[4:5], 1, v134
	s_andn2_b64 vcc, exec, s[0:1]
	s_waitcnt lgkmcnt(1)
	v_mfma_f32_32x32x16_bf16 v[32:47], v[144:147], v[72:75], v[32:47]
	s_waitcnt lgkmcnt(0)
	v_mfma_f32_32x32x16_bf16 v[48:63], v[148:151], v[72:75], v[48:63]
	ds_read_b128 v[144:147], v122
	ds_read_b128 v[148:151], v122 offset:4096
	s_waitcnt lgkmcnt(1)
	v_mfma_f32_32x32x16_bf16 v[32:47], v[144:147], v[68:71], v[32:47]
	s_waitcnt lgkmcnt(0)
	v_mfma_f32_32x32x16_bf16 v[48:63], v[148:151], v[68:71], v[48:63]
	ds_read_b128 v[144:147], v121
	ds_read_b128 v[148:151], v121 offset:4096
	s_waitcnt lgkmcnt(1)
	v_mfma_f32_32x32x16_bf16 v[32:47], v[144:147], v[64:67], v[32:47]
	v_add_u32_e32 v144, s13, v127
	s_waitcnt lgkmcnt(0)
	v_mfma_f32_32x32x16_bf16 v[48:63], v[148:151], v[64:67], v[48:63]
	s_nop 8
	v_mul_f32_e32 v33, 0x3e000000, v33
	s_cbranch_vccnz .LBB0_379
	v_add_u32_e32 v135, 1, v144
	v_add_u32_e32 v134, 0xffffff81, v143
	v_cmp_gt_u32_e32 vcc, s96, v135
	s_and_b64 s[16:17], s[8:9], vcc
	v_cmp_gt_i32_e32 vcc, s49, v134
	s_and_b64 vcc, s[16:17], vcc
	s_nop 0
	v_cndmask_b32_e32 v33, v169, v33, vcc
	s_and_b64 vcc, exec, s[4:5]
	v_mul_f32_e32 v34, 0x3e000000, v34
	s_cbranch_vccz .LBB0_380

.LBB0_377:
	v_add_u32_e32 v60, 0xffffff80, v143
	v_cmp_gt_u32_e32 vcc, s96, v144
	s_and_b64 s[4:5], s[8:9], vcc
	v_cmp_gt_i32_e32 vcc, s49, v60
	v_mul_f32_e32 v32, 0x3e000000, v32
	s_and_b64 vcc, s[4:5], vcc
	v_cndmask_b32_e32 v60, v169, v32, vcc
	v_cndmask_b32_e64 v32, v32, v60, s[0:1]
	s_mov_b32 s0, 0xf149f2ca
	v_max3_f32 v60, v32, s0, v33
	v_max3_f32 v60, v60, v34, v35
	v_max3_f32 v60, v60, v36, v37
	v_max3_f32 v60, v60, v38, v39
	v_max3_f32 v60, v60, v40, v41
	v_max3_f32 v60, v60, v42, v145
	v_max3_f32 v60, v60, v146, v147
	v_max3_f32 v60, v60, v148, v47
	v_max3_f32 v60, v60, v48, v49
	v_max3_f32 v60, v60, v50, v51
	v_max3_f32 v60, v60, v52, v53
	v_max3_f32 v60, v60, v54, v55
	v_max3_f32 v60, v60, v56, v57
	v_max3_f32 v60, v60, v58, v59
	v_max3_f32 v60, v60, v45, v46
	v_max3_f32 v60, v60, v44, v43
	ds_bpermute_b32 v61, v118, v60
	v_cmp_lt_f32_e32 vcc, s86, v32
	v_add_u32_e32 v143, 0x2000, v140
	s_add_i32 s13, s13, 64
	s_add_i32 s14, s14, 1
	s_waitcnt lgkmcnt(0)
	v_max3_f32 v144, v142, v60, v61
	v_sub_f32_e32 v61, v32, v144
	v_mul_f32_e32 v61, 0x3fb8aa3b, v61
	v_exp_f32_e32 v61, v61
	v_sub_f32_e32 v62, v33, v144
	v_mul_f32_e32 v62, 0x3fb8aa3b, v62
	v_exp_f32_e32 v62, v62
	v_cndmask_b32_e32 v61, 0, v61, vcc
	v_cmp_lt_f32_e32 vcc, s86, v33
	v_sub_f32_e32 v33, v34, v144
	v_mul_f32_e32 v33, 0x3fb8aa3b, v33
	v_exp_f32_e32 v33, v33
	v_cndmask_b32_e32 v62, 0, v62, vcc
	v_sub_f32_e32 v63, v35, v144
	v_cmp_lt_f32_e32 vcc, s86, v34
	v_mul_f32_e32 v63, 0x3fb8aa3b, v63
	v_exp_f32_e32 v63, v63
	v_cndmask_b32_e32 v134, 0, v33, vcc
	v_sub_f32_e32 v33, v36, v144
	v_mul_f32_e32 v33, 0x3fb8aa3b, v33
	v_sub_f32_e32 v34, v37, v144
	v_exp_f32_e32 v33, v33
	v_mul_f32_e32 v34, 0x3fb8aa3b, v34
	v_exp_f32_e32 v34, v34
	v_cmp_lt_f32_e32 vcc, s86, v35
	v_add_f32_e32 v32, 0, v61
	v_add_f32_e32 v32, v62, v32
	v_cndmask_b32_e32 v63, 0, v63, vcc
	v_cmp_lt_f32_e32 vcc, s86, v36
	v_add_f32_e32 v32, v134, v32
	v_add_f32_e32 v32, v63, v32
	v_cndmask_b32_e32 v135, 0, v33, vcc
	v_cmp_lt_f32_e32 vcc, s86, v37
	v_sub_f32_e32 v33, v38, v144
	v_mul_f32_e32 v33, 0x3fb8aa3b, v33
	v_cndmask_b32_e32 v136, 0, v34, vcc
	v_sub_f32_e32 v34, v39, v144
	v_exp_f32_e32 v33, v33
	v_mul_f32_e32 v34, 0x3fb8aa3b, v34
	v_exp_f32_e32 v34, v34
	v_cmp_lt_f32_e32 vcc, s86, v38
	v_add_f32_e32 v32, v135, v32
	v_add_f32_e32 v32, v136, v32
	v_cndmask_b32_e32 v137, 0, v33, vcc
	v_cmp_lt_f32_e32 vcc, s86, v39
	v_sub_f32_e32 v33, v40, v144
	v_mul_f32_e32 v33, 0x3fb8aa3b, v33
	v_cndmask_b32_e32 v39, 0, v34, vcc
	v_sub_f32_e32 v34, v41, v144
	v_exp_f32_e32 v33, v33
	v_mul_f32_e32 v34, 0x3fb8aa3b, v34
	v_exp_f32_e32 v34, v34
	v_cmp_lt_f32_e32 vcc, s86, v40
	v_add_f32_e32 v32, v137, v32
	v_add_f32_e32 v32, v39, v32
	v_cndmask_b32_e32 v40, 0, v33, vcc
	v_cmp_lt_f32_e32 vcc, s86, v41
	v_sub_f32_e32 v33, v42, v144
	v_mul_f32_e32 v33, 0x3fb8aa3b, v33
	v_cndmask_b32_e32 v41, 0, v34, vcc
	v_sub_f32_e32 v34, v145, v144
	v_exp_f32_e32 v33, v33
	v_mul_f32_e32 v34, 0x3fb8aa3b, v34
	v_exp_f32_e32 v34, v34
	v_cmp_lt_f32_e32 vcc, s86, v42
	v_add_f32_e32 v32, v40, v32
	v_add_f32_e32 v32, v41, v32
	v_cndmask_b32_e32 v42, 0, v33, vcc
	v_cmp_lt_f32_e32 vcc, s86, v145
	v_sub_f32_e32 v33, v146, v144
	v_mul_f32_e32 v33, 0x3fb8aa3b, v33
	v_cndmask_b32_e32 v145, 0, v34, vcc
	v_sub_f32_e32 v34, v147, v144
	v_exp_f32_e32 v33, v33
	v_mul_f32_e32 v34, 0x3fb8aa3b, v34
	v_exp_f32_e32 v34, v34
	v_cmp_lt_f32_e32 vcc, s86, v146
	v_add_f32_e32 v32, v42, v32
	v_add_f32_e32 v32, v145, v32
	v_cndmask_b32_e32 v146, 0, v33, vcc
	v_cmp_lt_f32_e32 vcc, s86, v147
	v_sub_f32_e32 v33, v148, v144
	v_mul_f32_e32 v33, 0x3fb8aa3b, v33
	v_cndmask_b32_e32 v147, 0, v34, vcc
	v_sub_f32_e32 v34, v47, v144
	v_exp_f32_e32 v33, v33
	v_mul_f32_e32 v34, 0x3fb8aa3b, v34
	v_exp_f32_e32 v34, v34
	v_cmp_lt_f32_e32 vcc, s86, v148
	v_add_f32_e32 v32, v146, v32
	v_add_f32_e32 v32, v147, v32
	v_cndmask_b32_e32 v148, 0, v33, vcc
	v_cmp_lt_f32_e32 vcc, s86, v47
	v_sub_f32_e32 v33, v48, v144
	v_mul_f32_e32 v33, 0x3fb8aa3b, v33
	v_cndmask_b32_e32 v47, 0, v34, vcc
	v_sub_f32_e32 v34, v49, v144
	v_exp_f32_e32 v33, v33
	v_mul_f32_e32 v34, 0x3fb8aa3b, v34
	v_exp_f32_e32 v34, v34
	v_cmp_lt_f32_e32 vcc, s86, v48
	v_add_f32_e32 v32, v148, v32
	v_add_f32_e32 v32, v47, v32
	v_cndmask_b32_e32 v149, 0, v33, vcc
	v_cmp_lt_f32_e32 vcc, s86, v49
	v_sub_f32_e32 v33, v50, v144
	v_mul_f32_e32 v33, 0x3fb8aa3b, v33
	v_cndmask_b32_e32 v150, 0, v34, vcc
	v_sub_f32_e32 v34, v51, v144
	v_exp_f32_e32 v33, v33
	v_mul_f32_e32 v34, 0x3fb8aa3b, v34
	v_exp_f32_e32 v34, v34
	v_cmp_lt_f32_e32 vcc, s86, v50
	v_add_f32_e32 v32, v149, v32
	v_add_f32_e32 v32, v150, v32
	v_cndmask_b32_e32 v151, 0, v33, vcc
	v_cmp_lt_f32_e32 vcc, s86, v51
	v_sub_f32_e32 v33, v52, v144
	v_mul_f32_e32 v33, 0x3fb8aa3b, v33
	v_cndmask_b32_e32 v152, 0, v34, vcc
	v_sub_f32_e32 v34, v53, v144
	v_exp_f32_e32 v33, v33
	v_mul_f32_e32 v34, 0x3fb8aa3b, v34
	v_exp_f32_e32 v34, v34
	v_cmp_lt_f32_e32 vcc, s86, v52
	v_add_f32_e32 v32, v151, v32
	v_add_f32_e32 v32, v152, v32
	v_cndmask_b32_e32 v153, 0, v33, vcc
	v_cmp_lt_f32_e32 vcc, s86, v53
	v_sub_f32_e32 v33, v54, v144
	v_mul_f32_e32 v33, 0x3fb8aa3b, v33
	v_cndmask_b32_e32 v53, 0, v34, vcc
	v_sub_f32_e32 v34, v55, v144
	v_exp_f32_e32 v33, v33
	v_mul_f32_e32 v34, 0x3fb8aa3b, v34
	v_exp_f32_e32 v34, v34
	v_cmp_lt_f32_e32 vcc, s86, v54
	v_add_f32_e32 v32, v153, v32
	v_add_f32_e32 v32, v53, v32
	v_cndmask_b32_e32 v54, 0, v33, vcc
	v_cmp_lt_f32_e32 vcc, s86, v55
	v_sub_f32_e32 v33, v56, v144
	v_mul_f32_e32 v33, 0x3fb8aa3b, v33
	v_cndmask_b32_e32 v55, 0, v34, vcc
	v_sub_f32_e32 v34, v57, v144
	v_exp_f32_e32 v33, v33
	v_mul_f32_e32 v34, 0x3fb8aa3b, v34
	v_exp_f32_e32 v34, v34
	v_cmp_lt_f32_e32 vcc, s86, v56
	v_add_f32_e32 v32, v54, v32
	v_add_f32_e32 v32, v55, v32
	v_cndmask_b32_e32 v56, 0, v33, vcc
	v_cmp_lt_f32_e32 vcc, s86, v57
	v_sub_f32_e32 v33, v58, v144
	v_mul_f32_e32 v33, 0x3fb8aa3b, v33
	v_cndmask_b32_e32 v57, 0, v34, vcc
	v_sub_f32_e32 v34, v59, v144
	v_exp_f32_e32 v33, v33
	v_mul_f32_e32 v34, 0x3fb8aa3b, v34
	v_exp_f32_e32 v34, v34
	v_add_f32_e32 v32, v56, v32
	v_cmp_lt_f32_e32 vcc, s86, v58
	v_add_f32_e32 v32, v57, v32
	v_sub_f32_e32 v60, v142, v144
	v_cndmask_b32_e32 v58, 0, v33, vcc
	v_cmp_lt_f32_e32 vcc, s86, v59
	v_add_f32_e32 v32, v58, v32
	v_mul_f32_e32 v60, 0x3fb8aa3b, v60
	v_cndmask_b32_e32 v59, 0, v34, vcc
	v_add_f32_e32 v154, v59, v32
	v_sub_f32_e32 v32, v45, v144
	v_mul_f32_e32 v32, 0x3fb8aa3b, v32
	v_exp_f32_e32 v52, v60
	v_exp_f32_e32 v60, v32
	ds_read_b64_tr_b16 v[32:33], v224 offset:8192
	ds_read_b64_tr_b16 v[34:35], v224 offset:9216
	v_add_u32_e32 v142, 0x3000, v140
	ds_read_b64_tr_b16 v[48:49], v225 offset:8192
	ds_read_b64_tr_b16 v[50:51], v225 offset:9216
	v_pk_mul_f32 v[30:31], v[30:31], v[52:53] op_sel_hi:[1,0]
	v_pk_mul_f32 v[28:29], v[28:29], v[52:53] op_sel_hi:[1,0]
	v_pk_mul_f32 v[26:27], v[26:27], v[52:53] op_sel_hi:[1,0]
	v_pk_mul_f32 v[24:25], v[24:25], v[52:53] op_sel_hi:[1,0]
	v_pk_mul_f32 v[22:23], v[22:23], v[52:53] op_sel_hi:[1,0]
	v_pk_mul_f32 v[20:21], v[20:21], v[52:53] op_sel_hi:[1,0]
	v_pk_mul_f32 v[18:19], v[18:19], v[52:53] op_sel_hi:[1,0]
	v_pk_mul_f32 v[16:17], v[16:17], v[52:53] op_sel_hi:[1,0]
	v_cvt_pk_bf16_f32 v36, v61, v62
	v_cvt_pk_bf16_f32 v37, v134, v63
	v_cvt_pk_bf16_f32 v38, v135, v136
	v_cvt_pk_bf16_f32 v39, v137, v39
	v_pk_mul_f32 v[14:15], v[14:15], v[52:53] op_sel_hi:[1,0]
	v_pk_mul_f32 v[12:13], v[12:13], v[52:53] op_sel_hi:[1,0]
	s_waitcnt lgkmcnt(2)
	v_mfma_f32_32x32x16_bf16 v[16:31], v[32:35], v[36:39], v[16:31]
	ds_read_b64_tr_b16 v[32:33], v224 offset:10240
	ds_read_b64_tr_b16 v[34:35], v224 offset:11264
	v_mul_f32_e64 v10, v10, v52
	v_mul_f32_e64 v11, v11, v52
	v_mul_f32_e64 v8, v8, v52
	v_mul_f32_e64 v9, v9, v52
	v_pk_mul_f32 v[6:7], v[6:7], v[52:53] op_sel_hi:[1,0]
	v_pk_mul_f32 v[4:5], v[4:5], v[52:53] op_sel_hi:[1,0]
	v_pk_mul_f32 v[2:3], v[2:3], v[52:53] op_sel_hi:[1,0]
	v_pk_mul_f32 v[0:1], v[0:1], v[52:53] op_sel_hi:[1,0]
	v_cmp_lt_f32_e32 vcc, s86, v45
	s_cmpk_lg_i32 s13, 0x240
	s_waitcnt lgkmcnt(2)
	v_mfma_f32_32x32x16_bf16 v[0:15], v[48:51], v[36:39], v[0:15]
	v_sub_f32_e32 v36, v46, v144
	v_mul_f32_e32 v36, 0x3fb8aa3b, v36
	v_exp_f32_e32 v48, v36
	v_cvt_pk_bf16_f32 v36, v40, v41
	v_cvt_pk_bf16_f32 v37, v42, v145
	v_cvt_pk_bf16_f32 v38, v146, v147
	v_cvt_pk_bf16_f32 v39, v148, v47
	v_cndmask_b32_e32 v42, 0, v60, vcc
	v_cmp_lt_f32_e32 vcc, s86, v46
	s_waitcnt lgkmcnt(0)
	v_mfma_f32_32x32x16_bf16 v[16:31], v[32:35], v[36:39], v[16:31]
	ds_read_b64_tr_b16 v[32:33], v225 offset:10240
	ds_read_b64_tr_b16 v[34:35], v225 offset:11264
	v_cndmask_b32_e32 v50, 0, v48, vcc
	ds_read_b64_tr_b16 v[46:47], v224 offset:12288
	ds_read_b64_tr_b16 v[48:49], v224 offset:13312
	v_sub_f32_e32 v41, v44, v144
	v_add_f32_e32 v40, v42, v154
	v_cmp_lt_f32_e32 vcc, s86, v44
	v_add_f32_e32 v40, v50, v40
	s_waitcnt lgkmcnt(2)
	v_mfma_f32_32x32x16_bf16 v[0:15], v[32:35], v[36:39], v[0:15]
	v_mul_f32_e32 v32, 0x3fb8aa3b, v41
	v_exp_f32_e32 v41, v32
	ds_read_b64_tr_b16 v[36:37], v225 offset:12288
	ds_read_b64_tr_b16 v[38:39], v225 offset:13312
	v_cvt_pk_bf16_f32 v32, v149, v150
	v_cvt_pk_bf16_f32 v33, v151, v152
	v_cvt_pk_bf16_f32 v34, v153, v53
	v_cvt_pk_bf16_f32 v35, v54, v55
	v_cvt_pk_bf16_f32 v42, v42, v50
	v_lshl_add_u64 v[114:115], v[114:115], 0, s[52:53]
	s_waitcnt lgkmcnt(2)
	v_mfma_f32_32x32x16_bf16 v[16:31], v[46:49], v[32:35], v[16:31]
	v_cndmask_b32_e32 v48, 0, v41, vcc
	v_add_f32_e32 v53, v48, v40
	v_sub_f32_e32 v40, v43, v144
	v_mul_f32_e32 v40, 0x3fb8aa3b, v40
	v_exp_f32_e32 v40, v40
	v_cmp_lt_f32_e32 vcc, s86, v43
	ds_read_b64_tr_b16 v[44:45], v224 offset:14336
	ds_read_b64_tr_b16 v[46:47], v224 offset:15360
	s_waitcnt lgkmcnt(2)
	v_mfma_f32_32x32x16_bf16 v[0:15], v[36:39], v[32:35], v[0:15]
	v_cndmask_b32_e32 v32, 0, v40, vcc
	v_cvt_pk_bf16_f32 v43, v48, v32
	ds_read_b64_tr_b16 v[48:49], v225 offset:14336
	ds_read_b64_tr_b16 v[50:51], v225 offset:15360
	v_cvt_pk_bf16_f32 v40, v56, v57
	v_cvt_pk_bf16_f32 v41, v58, v59
	s_waitcnt lgkmcnt(2)
	s_nop 0
	v_mfma_f32_32x32x16_bf16 v[16:31], v[44:47], v[40:43], v[16:31]
	v_add_f32_e32 v44, v32, v53
	ds_bpermute_b32 v45, v118, v44
	s_waitcnt lgkmcnt(0)
	v_add_f32_e32 v145, v44, v45
	v_mfma_f32_32x32x16_bf16 v[0:15], v[48:51], v[40:43], v[0:15]
	v_fmac_f32_e32 v145, v141, v52
	s_cbranch_scc0 .LBB0_409
	s_waitcnt vmcnt(0)
	v_mov_b64_e32 v[32:33], v[108:109]
	v_mov_b64_e32 v[36:37], v[104:105]
	v_mov_b64_e32 v[34:35], v[110:111]
	v_mov_b64_e32 v[38:39], v[106:107]
	v_mov_b32_e32 v142, v144
	v_mov_b32_e32 v141, v145
	v_mov_b64_e32 v[48:49], v[90:91]
	v_mov_b64_e32 v[50:51], v[88:89]
	v_mov_b64_e32 v[52:53], v[94:95]
	v_mov_b64_e32 v[54:55], v[92:93]
	v_mov_b64_e32 v[56:57], v[98:99]
	v_mov_b64_e32 v[58:59], v[96:97]
	v_mov_b64_e32 v[60:61], v[102:103]
	v_mov_b64_e32 v[62:63], v[100:101]
	s_cmp_lt_u32 s14, 6
	s_cselect_b64 s[0:1], -1, 0
	s_and_b64 vcc, exec, s[0:1]
	s_cbranch_vccnz .LBB0_340
	s_branch .LBB0_341

.LBB0_409:
	s_waitcnt vmcnt(0)
	v_cvt_pk_bf16_f32 v32, v108, v109
	v_cvt_pk_bf16_f32 v33, v110, v111
	v_cvt_pk_bf16_f32 v34, v104, v105
	v_cvt_pk_bf16_f32 v35, v106, v107
	v_cvt_pk_bf16_f32 v36, v84, v85
	v_cvt_pk_bf16_f32 v37, v86, v87
	v_cvt_pk_bf16_f32 v38, v80, v81
	v_cvt_pk_bf16_f32 v39, v82, v83
	v_cvt_pk_bf16_f32 v40, v100, v101
	v_cvt_pk_bf16_f32 v41, v102, v103
	v_cvt_pk_bf16_f32 v42, v96, v97
	v_cvt_pk_bf16_f32 v43, v98, v99
	v_cvt_pk_bf16_f32 v44, v92, v93
	v_cvt_pk_bf16_f32 v45, v94, v95
	v_cvt_pk_bf16_f32 v46, v88, v89
	v_cvt_pk_bf16_f32 v47, v90, v91
	s_barrier
	ds_write_b128 v125, v[32:35]
	ds_write_b128 v126, v[36:39]
	v_and_b32_e32 v223, 0xff, v160
	v_lshrrev_b32_e32 v224, 2, v223
	v_and_b32_e32 v225, 3, v223
	v_lshrrev_b32_e32 v226, 1, v225
	v_bfe_u32 v227, v224, 1, 1
	v_xor_b32_e32 v226, v226, v227
	v_lshlrev_b32_e32 v226, 6, v226
	v_and_b32_e32 v225, 1, v225
	v_lshl_or_b32 v226, v225, 5, v226
	v_lshl_add_u32 v226, v224, 7, v226
	v_add_u32_e32 v223, s78, v226
	v_and_b32_e32 v226, 63, v160
	v_lshrrev_b32_e32 v224, 5, v226
	v_bfe_u32 v227, v226, 2, 2
	v_lshl_add_u32 v224, v224, 2, v227
	v_lshlrev_b32_e32 v224, 7, v224
	v_bfe_u32 v227, v226, 3, 1
	v_lshl_or_b32 v224, v227, 6, v224
	v_bfe_u32 v227, v226, 4, 1
	v_lshl_or_b32 v224, v227, 5, v224
	v_and_b32_e32 v227, 3, v226
	v_lshl_or_b32 v224, v227, 3, v224
	v_add_u32_e32 v224, s78, v224
	v_xor_b32_e32 v225, 64, v224
	ds_write_b128 v223, v[40:43] offset:8192
	ds_write_b128 v223, v[44:47] offset:8208
	s_waitcnt lgkmcnt(0)
	s_barrier
	ds_read_b128 v[32:35], v124
	ds_read_b128 v[48:51], v124 offset:4096
	s_waitcnt lgkmcnt(1)
	v_mfma_f32_32x32x16_bf16 v[32:47], v[32:35], v[76:79], 0
	s_mov_b32 s0, 0x3e000000
	s_lshl_b32 s92, s10, 1
	v_lshlrev_b32_e32 v128, 1, v117
	s_waitcnt lgkmcnt(0)
	v_mfma_f32_32x32x16_bf16 v[48:63], v[48:51], v[76:79], 0
	ds_read_b128 v[76:79], v123
	ds_read_b128 v[80:83], v123 offset:4096
	s_waitcnt lgkmcnt(1)
	v_mfma_f32_32x32x16_bf16 v[32:47], v[76:79], v[72:75], v[32:47]
	s_waitcnt lgkmcnt(0)
	v_mfma_f32_32x32x16_bf16 v[48:63], v[80:83], v[72:75], v[48:63]
	ds_read_b128 v[72:75], v122
	ds_read_b128 v[76:79], v122 offset:4096
	s_waitcnt lgkmcnt(1)
	v_mfma_f32_32x32x16_bf16 v[32:47], v[72:75], v[68:71], v[32:47]
	s_waitcnt lgkmcnt(0)
	v_mfma_f32_32x32x16_bf16 v[48:63], v[76:79], v[68:71], v[48:63]
	ds_read_b128 v[68:71], v121 offset:4096
	ds_read_b128 v[72:75], v121
	s_waitcnt lgkmcnt(1)
	v_mfma_f32_32x32x16_bf16 v[48:63], v[68:71], v[64:67], v[48:63]
	s_waitcnt lgkmcnt(0)
	v_mfma_f32_32x32x16_bf16 v[32:47], v[72:75], v[64:67], v[32:47]
	s_nop 9
	v_mul_f32_e64 v62, v62, s0
	v_mul_f32_e64 v63, v63, s0
	v_mul_f32_e64 v60, v60, s0
	v_mul_f32_e64 v61, v61, s0
	v_mul_f32_e64 v58, v58, s0
	v_mul_f32_e64 v59, v59, s0
	v_pk_mul_f32 v[56:57], v[56:57], s[0:1] op_sel_hi:[1,0]
	v_pk_mul_f32 v[54:55], v[54:55], s[0:1] op_sel_hi:[1,0]
	v_pk_mul_f32 v[52:53], v[52:53], s[0:1] op_sel_hi:[1,0]
	v_pk_mul_f32 v[50:51], v[50:51], s[0:1] op_sel_hi:[1,0]
	v_pk_mul_f32 v[48:49], v[48:49], s[0:1] op_sel_hi:[1,0]
	v_pk_mul_f32 v[46:47], v[46:47], s[0:1] op_sel_hi:[1,0]
	v_pk_mul_f32 v[44:45], v[44:45], s[0:1] op_sel_hi:[1,0]
	v_pk_mul_f32 v[42:43], v[42:43], s[0:1] op_sel_hi:[1,0]
	v_pk_mul_f32 v[40:41], v[40:41], s[0:1] op_sel_hi:[1,0]
	v_pk_mul_f32 v[38:39], v[38:39], s[0:1] op_sel_hi:[1,0]
	v_pk_mul_f32 v[36:37], v[36:37], s[0:1] op_sel_hi:[1,0]
	v_pk_mul_f32 v[34:35], v[34:35], s[0:1] op_sel_hi:[1,0]
	v_pk_mul_f32 v[32:33], v[32:33], s[0:1] op_sel_hi:[1,0]
	s_mov_b32 s0, 0xf149f2ca
	v_max3_f32 v64, v32, s0, v33
	v_max3_f32 v64, v64, v34, v35
	v_max3_f32 v64, v64, v36, v37
	v_max3_f32 v64, v64, v38, v39
	v_max3_f32 v64, v64, v40, v41
	v_max3_f32 v64, v64, v42, v43
	v_max3_f32 v64, v64, v44, v45
	v_max3_f32 v64, v64, v46, v47
	v_max3_f32 v64, v64, v48, v49
	v_max3_f32 v64, v64, v50, v51
	v_max3_f32 v64, v64, v52, v53
	v_max3_f32 v64, v64, v54, v55
	v_max3_f32 v64, v64, v56, v57
	v_max3_f32 v64, v64, v58, v59
	v_max3_f32 v64, v64, v60, v61
	v_max3_f32 v64, v64, v62, v63
	ds_bpermute_b32 v65, v118, v64
	v_cmp_lt_f32_e32 vcc, s86, v33
	s_waitcnt lgkmcnt(0)
	v_max3_f32 v64, v144, v64, v65
	v_sub_f32_e32 v67, v33, v64
	v_sub_f32_e32 v66, v32, v64
	v_mul_f32_e32 v67, 0x3fb8aa3b, v67
	v_exp_f32_e32 v67, v67
	v_mul_f32_e32 v66, 0x3fb8aa3b, v66
	v_sub_f32_e32 v68, v35, v64
	v_exp_f32_e32 v66, v66
	v_sub_f32_e32 v33, v34, v64
	v_mul_f32_e32 v68, 0x3fb8aa3b, v68
	v_exp_f32_e32 v68, v68
	v_mul_f32_e32 v33, 0x3fb8aa3b, v33
	v_exp_f32_e32 v33, v33
	v_cndmask_b32_e32 v67, 0, v67, vcc
	v_cmp_lt_f32_e32 vcc, s86, v32
	v_sub_f32_e32 v65, v144, v64
	v_mul_f32_e32 v65, 0x3fb8aa3b, v65
	v_cndmask_b32_e32 v66, 0, v66, vcc
	v_cmp_lt_f32_e32 vcc, s86, v35
	v_add_f32_e32 v32, 0, v66
	v_add_f32_e32 v32, v67, v32
	v_cndmask_b32_e32 v68, 0, v68, vcc
	v_cmp_lt_f32_e32 vcc, s86, v34
	v_sub_f32_e32 v34, v37, v64
	v_mul_f32_e32 v34, 0x3fb8aa3b, v34
	v_cndmask_b32_e32 v69, 0, v33, vcc
	v_sub_f32_e32 v33, v36, v64
	v_exp_f32_e32 v34, v34
	v_mul_f32_e32 v33, 0x3fb8aa3b, v33
	v_exp_f32_e32 v33, v33
	v_cmp_lt_f32_e32 vcc, s86, v37
	v_add_f32_e32 v32, v69, v32
	v_add_f32_e32 v32, v68, v32
	v_cndmask_b32_e32 v70, 0, v34, vcc
	v_cmp_lt_f32_e32 vcc, s86, v36
	v_sub_f32_e32 v34, v39, v64
	v_mul_f32_e32 v34, 0x3fb8aa3b, v34
	v_cndmask_b32_e32 v71, 0, v33, vcc
	v_sub_f32_e32 v33, v38, v64
	v_exp_f32_e32 v34, v34
	v_mul_f32_e32 v33, 0x3fb8aa3b, v33
	v_exp_f32_e32 v33, v33
	v_cmp_lt_f32_e32 vcc, s86, v39
	v_add_f32_e32 v32, v71, v32
	v_add_f32_e32 v32, v70, v32
	v_cndmask_b32_e32 v39, 0, v34, vcc
	v_cmp_lt_f32_e32 vcc, s86, v38
	v_sub_f32_e32 v34, v41, v64
	v_mul_f32_e32 v34, 0x3fb8aa3b, v34
	v_cndmask_b32_e32 v72, 0, v33, vcc
	v_sub_f32_e32 v33, v40, v64
	v_exp_f32_e32 v34, v34
	v_mul_f32_e32 v33, 0x3fb8aa3b, v33
	v_exp_f32_e32 v33, v33
	v_cmp_lt_f32_e32 vcc, s86, v41
	v_add_f32_e32 v32, v72, v32
	v_add_f32_e32 v32, v39, v32
	v_cndmask_b32_e32 v73, 0, v34, vcc
	v_cmp_lt_f32_e32 vcc, s86, v40
	v_sub_f32_e32 v34, v43, v64
	v_mul_f32_e32 v34, 0x3fb8aa3b, v34
	v_cndmask_b32_e32 v74, 0, v33, vcc
	v_sub_f32_e32 v33, v42, v64
	v_exp_f32_e32 v34, v34
	v_mul_f32_e32 v33, 0x3fb8aa3b, v33
	v_exp_f32_e32 v33, v33
	v_cmp_lt_f32_e32 vcc, s86, v43
	v_add_f32_e32 v32, v74, v32
	v_add_f32_e32 v32, v73, v32
	v_cndmask_b32_e32 v75, 0, v34, vcc
	v_cmp_lt_f32_e32 vcc, s86, v42
	v_sub_f32_e32 v34, v45, v64
	v_mul_f32_e32 v34, 0x3fb8aa3b, v34
	v_cndmask_b32_e32 v76, 0, v33, vcc
	v_sub_f32_e32 v33, v44, v64
	v_exp_f32_e32 v34, v34
	v_mul_f32_e32 v33, 0x3fb8aa3b, v33
	v_exp_f32_e32 v33, v33
	v_cmp_lt_f32_e32 vcc, s86, v45
	v_add_f32_e32 v32, v76, v32
	v_add_f32_e32 v32, v75, v32
	v_cndmask_b32_e32 v45, 0, v34, vcc
	v_cmp_lt_f32_e32 vcc, s86, v44
	v_sub_f32_e32 v34, v47, v64
	v_mul_f32_e32 v34, 0x3fb8aa3b, v34
	v_cndmask_b32_e32 v77, 0, v33, vcc
	v_sub_f32_e32 v33, v46, v64
	v_exp_f32_e32 v34, v34
	v_mul_f32_e32 v33, 0x3fb8aa3b, v33
	v_exp_f32_e32 v33, v33
	v_cmp_lt_f32_e32 vcc, s86, v47
	v_add_f32_e32 v32, v77, v32
	v_add_f32_e32 v32, v45, v32
	v_cndmask_b32_e32 v47, 0, v34, vcc
	v_cmp_lt_f32_e32 vcc, s86, v46
	v_sub_f32_e32 v34, v49, v64
	v_mul_f32_e32 v34, 0x3fb8aa3b, v34
	v_cndmask_b32_e32 v46, 0, v33, vcc
	v_sub_f32_e32 v33, v48, v64
	v_exp_f32_e32 v34, v34
	v_mul_f32_e32 v33, 0x3fb8aa3b, v33
	v_exp_f32_e32 v33, v33
	v_cmp_lt_f32_e32 vcc, s86, v49
	v_add_f32_e32 v32, v46, v32
	v_add_f32_e32 v32, v47, v32
	v_cndmask_b32_e32 v49, 0, v34, vcc
	v_cmp_lt_f32_e32 vcc, s86, v48
	v_sub_f32_e32 v34, v51, v64
	v_mul_f32_e32 v34, 0x3fb8aa3b, v34
	v_cndmask_b32_e32 v48, 0, v33, vcc
	v_sub_f32_e32 v33, v50, v64
	v_exp_f32_e32 v34, v34
	v_mul_f32_e32 v33, 0x3fb8aa3b, v33
	v_exp_f32_e32 v33, v33
	v_cmp_lt_f32_e32 vcc, s86, v51
	v_add_f32_e32 v32, v48, v32
	v_add_f32_e32 v32, v49, v32
	v_cndmask_b32_e32 v51, 0, v34, vcc
	v_cmp_lt_f32_e32 vcc, s86, v50
	v_sub_f32_e32 v34, v53, v64
	v_mul_f32_e32 v34, 0x3fb8aa3b, v34
	v_cndmask_b32_e32 v50, 0, v33, vcc
	v_sub_f32_e32 v33, v52, v64
	v_exp_f32_e32 v34, v34
	v_mul_f32_e32 v33, 0x3fb8aa3b, v33
	v_exp_f32_e32 v33, v33
	v_cmp_lt_f32_e32 vcc, s86, v53
	v_add_f32_e32 v32, v50, v32
	v_add_f32_e32 v32, v51, v32
	v_cndmask_b32_e32 v53, 0, v34, vcc
	v_cmp_lt_f32_e32 vcc, s86, v52
	v_sub_f32_e32 v34, v55, v64
	v_mul_f32_e32 v34, 0x3fb8aa3b, v34
	v_cndmask_b32_e32 v52, 0, v33, vcc
	v_sub_f32_e32 v33, v54, v64
	v_exp_f32_e32 v34, v34
	v_mul_f32_e32 v33, 0x3fb8aa3b, v33
	v_exp_f32_e32 v33, v33
	v_cmp_lt_f32_e32 vcc, s86, v55
	v_add_f32_e32 v32, v52, v32
	v_add_f32_e32 v32, v53, v32
	v_cndmask_b32_e32 v55, 0, v34, vcc
	v_cmp_lt_f32_e32 vcc, s86, v54
	v_sub_f32_e32 v34, v57, v64
	v_mul_f32_e32 v34, 0x3fb8aa3b, v34
	v_cndmask_b32_e32 v54, 0, v33, vcc
	v_sub_f32_e32 v33, v56, v64
	v_exp_f32_e32 v34, v34
	v_mul_f32_e32 v33, 0x3fb8aa3b, v33
	v_exp_f32_e32 v33, v33
	v_cmp_lt_f32_e32 vcc, s86, v57
	v_add_f32_e32 v32, v54, v32
	v_add_f32_e32 v32, v55, v32
	v_cndmask_b32_e32 v57, 0, v34, vcc
	v_cmp_lt_f32_e32 vcc, s86, v56
	v_sub_f32_e32 v34, v59, v64
	v_mul_f32_e32 v34, 0x3fb8aa3b, v34
	v_cndmask_b32_e32 v56, 0, v33, vcc
	v_sub_f32_e32 v33, v58, v64
	v_exp_f32_e32 v34, v34
	v_mul_f32_e32 v33, 0x3fb8aa3b, v33
	v_exp_f32_e32 v33, v33
	v_cmp_lt_f32_e32 vcc, s86, v59
	v_add_f32_e32 v32, v56, v32
	v_add_f32_e32 v32, v57, v32
	v_cndmask_b32_e32 v59, 0, v34, vcc
	v_cmp_lt_f32_e32 vcc, s86, v58
	v_sub_f32_e32 v34, v61, v64
	v_mul_f32_e32 v34, 0x3fb8aa3b, v34
	v_cndmask_b32_e32 v58, 0, v33, vcc
	v_sub_f32_e32 v33, v60, v64
	v_exp_f32_e32 v34, v34
	v_mul_f32_e32 v33, 0x3fb8aa3b, v33
	v_exp_f32_e32 v33, v33
	v_cmp_lt_f32_e32 vcc, s86, v61
	v_add_f32_e32 v32, v58, v32
	v_add_f32_e32 v32, v59, v32
	v_cndmask_b32_e32 v61, 0, v34, vcc
	v_cmp_lt_f32_e32 vcc, s86, v60
	v_exp_f32_e32 v44, v65
	ds_read_b64_tr_b16 v[40:41], v225 offset:8192
	ds_read_b64_tr_b16 v[42:43], v225 offset:9216
	v_cndmask_b32_e32 v60, 0, v33, vcc
	v_add_f32_e32 v65, v60, v32
	ds_read_b64_tr_b16 v[32:33], v224 offset:8192
	ds_read_b64_tr_b16 v[34:35], v224 offset:9216
	v_pk_mul_f32 v[30:31], v[30:31], v[44:45] op_sel_hi:[1,0]
	v_pk_mul_f32 v[28:29], v[28:29], v[44:45] op_sel_hi:[1,0]
	v_pk_mul_f32 v[26:27], v[26:27], v[44:45] op_sel_hi:[1,0]
	v_pk_mul_f32 v[24:25], v[24:25], v[44:45] op_sel_hi:[1,0]
	v_pk_mul_f32 v[22:23], v[22:23], v[44:45] op_sel_hi:[1,0]
	v_pk_mul_f32 v[20:21], v[20:21], v[44:45] op_sel_hi:[1,0]
	v_pk_mul_f32 v[18:19], v[18:19], v[44:45] op_sel_hi:[1,0]
	v_pk_mul_f32 v[16:17], v[16:17], v[44:45] op_sel_hi:[1,0]
	v_cvt_pk_bf16_f32 v36, v66, v67
	v_cvt_pk_bf16_f32 v37, v69, v68
	v_cvt_pk_bf16_f32 v38, v71, v70
	v_cvt_pk_bf16_f32 v39, v72, v39
	v_pk_mul_f32 v[14:15], v[14:15], v[44:45] op_sel_hi:[1,0]
	v_pk_mul_f32 v[12:13], v[12:13], v[44:45] op_sel_hi:[1,0]
	s_waitcnt lgkmcnt(0)
	v_mfma_f32_32x32x16_bf16 v[16:31], v[32:35], v[36:39], v[16:31]
	ds_read_b64_tr_b16 v[32:33], v224 offset:10240
	ds_read_b64_tr_b16 v[34:35], v224 offset:11264
	v_mul_f32_e64 v10, v10, v44
	v_mul_f32_e64 v11, v11, v44
	v_mul_f32_e64 v8, v8, v44
	v_mul_f32_e64 v9, v9, v44
	v_pk_mul_f32 v[6:7], v[6:7], v[44:45] op_sel_hi:[1,0]
	v_pk_mul_f32 v[4:5], v[4:5], v[44:45] op_sel_hi:[1,0]
	v_pk_mul_f32 v[2:3], v[2:3], v[44:45] op_sel_hi:[1,0]
	v_pk_mul_f32 v[0:1], v[0:1], v[44:45] op_sel_hi:[1,0]
	v_sub_f32_e32 v66, v62, v64
	v_cmp_lt_f32_e32 vcc, s86, v63
	v_mfma_f32_32x32x16_bf16 v[0:15], v[40:43], v[36:39], v[0:15]
	ds_read_b64_tr_b16 v[40:41], v225 offset:10240
	ds_read_b64_tr_b16 v[42:43], v225 offset:11264
	v_cvt_pk_bf16_f32 v36, v74, v73
	v_cvt_pk_bf16_f32 v37, v76, v75
	v_cvt_pk_bf16_f32 v38, v77, v45
	v_cvt_pk_bf16_f32 v39, v46, v47
	v_add_f32_e32 v65, v61, v65
	s_waitcnt lgkmcnt(2)
	v_mfma_f32_32x32x16_bf16 v[16:31], v[32:35], v[36:39], v[16:31]
	v_sub_f32_e32 v32, v63, v64
	v_mul_f32_e32 v32, 0x3fb8aa3b, v32
	v_exp_f32_e32 v32, v32
	v_mul_f32_e32 v33, 0x3fb8aa3b, v66
	v_exp_f32_e32 v45, v33
	v_cndmask_b32_e32 v46, 0, v32, vcc
	s_waitcnt lgkmcnt(0)
	v_mfma_f32_32x32x16_bf16 v[0:15], v[40:43], v[36:39], v[0:15]
	ds_read_b64_tr_b16 v[32:33], v224 offset:12288
	ds_read_b64_tr_b16 v[34:35], v224 offset:13312
	ds_read_b64_tr_b16 v[40:41], v225 offset:12288
	ds_read_b64_tr_b16 v[42:43], v225 offset:13312
	v_cmp_lt_f32_e32 vcc, s86, v62
	v_cvt_pk_bf16_f32 v36, v48, v49
	v_cvt_pk_bf16_f32 v37, v50, v51
	v_cndmask_b32_e32 v45, 0, v45, vcc
	v_add_f32_e32 v47, v45, v65
	v_cvt_pk_bf16_f32 v38, v52, v53
	v_cvt_pk_bf16_f32 v39, v54, v55
	s_waitcnt lgkmcnt(2)
	s_nop 0
	v_mfma_f32_32x32x16_bf16 v[16:31], v[32:35], v[36:39], v[16:31]
	v_add_f32_e32 v32, v46, v47
	ds_bpermute_b32 v33, v118, v32
	v_cvt_pk_bf16_f32 v35, v45, v46
	v_cvt_pk_bf16_f32 v34, v60, v61
	s_waitcnt lgkmcnt(0)
	v_add_f32_e32 v47, v32, v33
	v_mfma_f32_32x32x16_bf16 v[0:15], v[40:43], v[36:39], v[0:15]
	ds_read_b64_tr_b16 v[36:37], v224 offset:14336
	ds_read_b64_tr_b16 v[38:39], v224 offset:15360
	v_max_f32_e32 v40, v116, v116
	v_max_f32_e32 v40, v64, v40
	v_sub_f32_e32 v41, v64, v40
	v_sub_f32_e32 v40, v116, v40
	v_mul_f32_e32 v41, 0x3fb8aa3b, v41
	v_mul_f32_e32 v40, 0x3fb8aa3b, v40
	v_exp_f32_e32 v45, v41
	v_exp_f32_e32 v46, v40
	ds_read_b64_tr_b16 v[40:41], v225 offset:14336
	ds_read_b64_tr_b16 v[42:43], v225 offset:15360
	v_fmac_f32_e32 v47, v145, v44
	v_cvt_pk_bf16_f32 v32, v56, v57
	v_cvt_pk_bf16_f32 v33, v58, v59
	v_fmac_f32_e32 v46, v45, v47
	s_waitcnt lgkmcnt(2)
	v_mfma_f32_32x32x16_bf16 v[16:31], v[36:39], v[32:35], v[16:31]
	v_div_scale_f32 v36, s[0:1], v46, v46, v45
	v_rcp_f32_e32 v37, v36
	v_readlane_b32 s0, v254, 43
	v_readlane_b32 s1, v254, 44
	s_waitcnt lgkmcnt(0)
	v_mfma_f32_32x32x16_bf16 v[0:15], v[40:43], v[32:35], v[0:15]
	v_fma_f32 v32, -v36, v37, 1.0
	v_fmac_f32_e32 v37, v32, v37
	v_div_scale_f32 v32, vcc, v45, v46, v45
	v_mul_f32_e32 v33, v32, v37
	v_fma_f32 v34, -v36, v33, v32
	v_fmac_f32_e32 v33, v34, v37
	v_fma_f32 v32, -v36, v33, v32
	v_div_fmas_f32 v32, v32, v37, v33
	v_lshlrev_b64 v[34:35], 11, v[112:113]
	v_div_fixup_f32 v32, v32, v46, v45
	v_lshl_add_u64 v[34:35], s[0:1], 0, v[34:35]
	v_lshl_add_u64 v[34:35], v[34:35], 0, s[92:93]
	v_pk_mul_f32 v[16:17], v[16:17], v[32:33] op_sel_hi:[1,0]
	v_pk_mul_f32 v[18:19], v[18:19], v[32:33] op_sel_hi:[1,0]
	v_cvt_pk_bf16_f32 v16, v16, v17
	v_cvt_pk_bf16_f32 v17, v18, v19
	v_lshl_add_u64 v[18:19], v[34:35], 0, v[128:129]
	s_mov_b64 s[0:1], 0x153ca600
	v_lshl_add_u64 v[34:35], v[18:19], 0, s[0:1]
	s_mov_b32 s0, 0x153ca000
	v_add_co_u32_e32 v18, vcc, s0, v18
	v_pk_mul_f32 v[0:1], v[0:1], v[32:33] op_sel_hi:[1,0]
	v_pk_mul_f32 v[2:3], v[2:3], v[32:33] op_sel_hi:[1,0]
	v_addc_co_u32_e32 v19, vcc, 0, v19, vcc
	v_cvt_pk_bf16_f32 v0, v0, v1
	v_cvt_pk_bf16_f32 v1, v2, v3
	global_store_dwordx2 v[18:19], v[16:17], off offset:1536
	v_pk_mul_f32 v[16:17], v[20:21], v[32:33] op_sel_hi:[1,0]
	v_pk_mul_f32 v[18:19], v[22:23], v[32:33] op_sel_hi:[1,0]
	global_store_dwordx2 v[34:35], v[0:1], off offset:64
	v_pk_mul_f32 v[0:1], v[4:5], v[32:33] op_sel_hi:[1,0]
	v_pk_mul_f32 v[2:3], v[6:7], v[32:33] op_sel_hi:[1,0]
	v_cvt_pk_bf16_f32 v16, v16, v17
	v_cvt_pk_bf16_f32 v17, v18, v19
	v_cvt_pk_bf16_f32 v0, v0, v1
	v_cvt_pk_bf16_f32 v1, v2, v3
	global_store_dwordx2 v[34:35], v[16:17], off offset:16
	v_pk_mul_f32 v[16:17], v[24:25], v[32:33] op_sel_hi:[1,0]
	v_pk_mul_f32 v[18:19], v[26:27], v[32:33] op_sel_hi:[1,0]
	global_store_dwordx2 v[34:35], v[0:1], off offset:80
	v_pk_mul_f32 v[0:1], v[8:9], v[32:33] op_sel_hi:[1,0]
	v_pk_mul_f32 v[2:3], v[10:11], v[32:33] op_sel_hi:[1,0]
	v_cvt_pk_bf16_f32 v16, v16, v17
	v_cvt_pk_bf16_f32 v17, v18, v19
	v_cvt_pk_bf16_f32 v0, v0, v1
	v_cvt_pk_bf16_f32 v1, v2, v3
	global_store_dwordx2 v[34:35], v[16:17], off offset:32
	v_pk_mul_f32 v[16:17], v[28:29], v[32:33] op_sel_hi:[1,0]
	v_pk_mul_f32 v[18:19], v[30:31], v[32:33] op_sel_hi:[1,0]
	global_store_dwordx2 v[34:35], v[0:1], off offset:96
	v_pk_mul_f32 v[0:1], v[12:13], v[32:33] op_sel_hi:[1,0]
	v_pk_mul_f32 v[2:3], v[14:15], v[32:33] op_sel_hi:[1,0]
	v_cvt_pk_bf16_f32 v16, v16, v17
	v_cvt_pk_bf16_f32 v17, v18, v19
	v_cvt_pk_bf16_f32 v0, v0, v1
	v_cvt_pk_bf16_f32 v1, v2, v3
	global_store_dwordx2 v[34:35], v[16:17], off offset:48
	global_store_dwordx2 v[34:35], v[0:1], off offset:112
	s_barrier
